# window for L0 FFN2 gate/up takes 8 items per WG (no mini GEMM there), others 7
# speedup vs baseline: 1.0134x; 1.0016x over previous
; __device__ __forceinline__ unsigned cvt_pk_bf16(float lo, float hi) { unsigned r; asm volatile("v_cvt_pk_bf16_f32 %0, %1, %2" : "=v"(r) : "v"(lo), "v"(hi)); return r; }
; #define LAS __attribute__((address_space(3)))
; __device__ __forceinline__ void tr_item_cu(const float* __restrict__ W, int K, int N, bf16* __restrict__ WT, const float* rowgain, int mode, LAS unsigned char* buf, int item, int wave, int lane) {
;     const int nblk = N >> 7, kb = item / nblk, nb = item - kb * nblk, k0 = 256 * kb, n0 = 128 * nb;
;     const int hr = lane >> 5, c = lane & 31, kw = 32 * wave + 16 * hr;
;     f32x4 v[16];
;     const float* src = W + (size_t)(k0 + kw) * N + n0 + 4 * c;
; #pragma unroll
;     for (int j = 0; j < 16; ++j) v[j] = __builtin_nontemporal_load((const f32x4*)(src + (size_t)j * N));
;     if (rowgain) {
; #pragma unroll
;         for (int q = 0; q < 4; ++q) { const f32x4 r4 = *(const f32x4*)(rowgain + k0 + kw + 4 * q);
; #pragma unroll
;             for (int e = 0; e < 4; ++e) v[4 * q + e] = v[4 * q + e] * r4[e]; }
;     }
; #pragma unroll
;     for (int i = 0; i < 4; ++i) {
;         u32x4 lo, hi;
;         lo.x = pg8::cvt_pk_bf16(v[0][i], v[1][i]);   lo.y = pg8::cvt_pk_bf16(v[2][i], v[3][i]);   lo.z = pg8::cvt_pk_bf16(v[4][i], v[5][i]);   lo.w = pg8::cvt_pk_bf16(v[6][i], v[7][i]);
;         hi.x = pg8::cvt_pk_bf16(v[8][i], v[9][i]);   hi.y = pg8::cvt_pk_bf16(v[10][i], v[11][i]); hi.z = pg8::cvt_pk_bf16(v[12][i], v[13][i]); hi.w = pg8::cvt_pk_bf16(v[14][i], v[15][i]);
;         LAS unsigned char* p = buf + (4 * c + i) * TCP + kw * 2;
;         *(LAS u32x4*)p = lo; *(LAS u32x4*)(p + 16) = hi;
;     }
;     __syncthreads();
; #pragma unroll
;     for (int m = 0; m < 8; ++m) { const int row = 16 * wave + 2 * m + hr;
;         const u32x4 o = *(const LAS u32x4*)(buf + row * TCP + c * 16);
;         asm volatile("global_store_dwordx4 %0, %1, off sc1\n\ts_nop 1" :: "v"(WT + (size_t)row_map(mode, n0 + row) * K + k0 + 8 * c), "v"(o) : "memory"); }
.Ldc_pre:
	v_ashrrev_i32_e32 v3, 5, v2
	v_lshl_add_u32 v77, s73, 4, v3
	v_add_u32_e32 v82, 2, v77
	v_lshrrev_b32_e32 v6, 2, v82
	v_and_b32_e32 v84, 16, v6
	v_lshlrev_b32_e32 v6, 2, v82
	v_and_b32_e32 v6, 16, v6
	v_lshrrev_b32_e32 v7, 1, v82
	v_add_u32_e32 v86, 4, v77
	v_and_or_b32 v85, v7, 12, v6
	v_lshrrev_b32_e32 v6, 2, v86
	v_and_b32_e32 v88, 16, v6
	v_lshlrev_b32_e32 v6, 2, v86
	v_and_b32_e32 v6, 16, v6
	v_lshrrev_b32_e32 v7, 1, v86
	v_add_u32_e32 v90, 6, v77
	v_and_or_b32 v89, v7, 12, v6
	v_lshrrev_b32_e32 v6, 2, v90
	v_and_b32_e32 v92, 16, v6
	v_lshlrev_b32_e32 v6, 2, v90
	v_and_b32_e32 v6, 16, v6
	v_lshrrev_b32_e32 v7, 1, v90
	v_add_u32_e32 v97, 10, v77
	v_and_or_b32 v93, v7, 12, v6
	v_lshrrev_b32_e32 v7, 2, v97
	s_add_u32 s36, s12, 0x900000
	v_and_b32_e32 v99, 16, v7
	v_lshlrev_b32_e32 v7, 2, v97
	s_addc_u32 s37, s13, 0
	s_load_dwordx2 s[12:13], s[0:1], 0x8
	s_load_dwordx4 s[4:7], s[0:1], 0x20
	s_load_dwordx4 s[8:11], s[0:1], 0x58
	s_load_dwordx2 s[14:15], s[0:1], 0x30
	s_load_dwordx2 s[16:17], s[0:1], 0x78
	v_and_b32_e32 v7, 16, v7
	v_lshrrev_b32_e32 v8, 1, v97
	v_add_u32_e32 v101, 12, v77
	v_and_or_b32 v100, v8, 12, v7
	v_lshrrev_b32_e32 v7, 2, v101
	v_and_b32_e32 v103, 16, v7
	v_lshlrev_b32_e32 v7, 2, v101
	v_and_b32_e32 v7, 16, v7
	v_lshrrev_b32_e32 v8, 1, v101
	v_add_u32_e32 v105, 14, v77
	s_lshl_b32 s18, s73, 5
	v_add_u32_e32 v94, 8, v77
	v_and_or_b32 v104, v8, 12, v7
	v_lshrrev_b32_e32 v7, 2, v105
	v_and_b32_e32 v4, 31, v2
	v_lshl_add_u32 v66, v3, 4, s18
	v_lshrrev_b32_e32 v5, 2, v77
	v_lshlrev_b32_e32 v3, 2, v3
	v_lshrrev_b32_e32 v6, 2, v94
	v_and_b32_e32 v107, 16, v7
	v_lshlrev_b32_e32 v7, 2, v105
	v_lshlrev_b32_e32 v2, 2, v4
	v_mov_b32_e32 v69, 0
	v_mul_u32_u24_e32 v76, 0x840, v4
	v_lshlrev_b32_e32 v78, 4, v4
	v_lshlrev_b32_e32 v4, 3, v4
	s_movk_i32 s18, 0x210
	v_and_b32_e32 v80, 0x7f, v77
	v_and_b32_e32 v81, 16, v5
	v_and_b32_e32 v3, 16, v3
	v_lshrrev_b32_e32 v5, 1, v77
	v_and_b32_e32 v83, 0x7f, v82
	v_and_b32_e32 v87, 0x7f, v86
	v_and_b32_e32 v91, 0x7f, v90
	v_and_b32_e32 v95, 0x7f, v94
	v_and_b32_e32 v96, 16, v6
	v_lshrrev_b32_e32 v6, 1, v94
	v_and_b32_e32 v98, 0x7f, v97
	v_and_b32_e32 v102, 0x7f, v101
	v_and_b32_e32 v106, 0x7f, v105
	v_and_b32_e32 v7, 16, v7
	v_lshrrev_b32_e32 v8, 1, v105
	v_ashrrev_i32_e32 v67, 31, v66
	v_lshlrev_b32_e32 v75, 1, v66
	v_mul_lo_u32 v79, v77, s18
	v_and_or_b32 v108, v8, 12, v7
	v_or_b32_e32 v109, 0x80, v80
	v_or_b32_e32 v110, 0x80, v83
	v_or_b32_e32 v111, 0x80, v87
	v_or_b32_e32 v112, 0x80, v91
	v_or_b32_e32 v113, 0x80, v95
	v_or_b32_e32 v114, 0x80, v98
	v_or_b32_e32 v115, 0x80, v102
	v_or_b32_e32 v116, 0x80, v106
	v_and_or_b32 v117, v5, 12, v3
	v_and_or_b32 v118, v6, 12, v3
	s_mov_b32 s19, 0
	s_sub_i32 s38, 0, s72
	s_sub_i32 s39, 0x137f, s72
	v_lshlrev_b32_e32 v70, 2, v2
	v_mov_b32_e32 v71, v69
	s_movk_i32 s40, 0xff00
	s_movk_i32 s41, 0xf7ff
	s_movk_i32 s42, 0xffe3
	v_lshlrev_b32_e32 v68, 1, v4
	s_mov_b32 s43, 0
	s_mov_b32 s44, s72
	s_cmp_lg_u32 s98, 0
	s_cbranch_scc1 .Ldc_ovr
	v_readlane_b32 s100, v254, 2
	s_movk_i32 s101, 0x137f
	s_nop 1
	s_mov_b32 s99, s100
	s_cmpk_lg_i32 s100, 0x100
	s_cbranch_scc1 .LBB0_33
	s_cmpk_lt_i32 s72, 0x80
	s_cbranch_scc1 .Ldc_lowhalf
	s_addk_i32 s44, 3168
	s_sub_i32 s38, 0, s44
	s_sub_i32 s39, 0x137f, s44
	s_branch .LBB0_33
.Ldc_lowhalf:
	s_addk_i32 s44, 2496
	s_sub_i32 s38, 0, s44
	s_sub_i32 s39, 0x137f, s44
	s_movk_i32 s100, 928
	s_branch .LBB0_33

; __global__ void __launch_bounds__(NTHREADS, 2) mega_fwd(Args args) {
;     ...
;         for (int it = bid; it < DEPTH * I_LAYER; it += G, nbuf ^= 1) {
;             const int itr = DEPTH * I_LAYER - 1 - it;
;             const int l = itr / I_LAYER; int r = itr - l * I_LAYER;
;             unsigned char* WL = P_WL(l);
;             const float* W; int K, N, mode = 0; bf16* WT; const float* rg = nullptr;
;             if (r < 3 * I_GU) { const int w = r / I_GU; r -= w * I_GU;
;                 if (w < 2) { W = args.in[2 + w] + (size_t)l * D * FF; K = D; N = FF; WT = (bf16*)(WL + OFF_WGU1); rg = args.in[1] + (size_t)l * D; mode = 1 + w; }
;                 else { W = args.in[4] + (size_t)l * FF * D; K = FF; N = D; WT = (bf16*)(WL + OFF_WD1); } }
;             else if ((r -= 3 * I_GU) < 3 * I_GU) { const int w = r / I_GU; r -= w * I_GU;
;                 if (w < 2) { W = args.in[13 + w] + (size_t)l * D * FF; K = D; N = FF; WT = (bf16*)(WL + OFF_WGU2); rg = args.in[12] + (size_t)l * D; mode = 1 + w; }
;                 else { W = args.in[15] + (size_t)l * FF * D; K = FF; N = D; WT = (bf16*)(WL + OFF_WD2); } }
;             else if ((r -= 3 * I_GU) < I_IN) { W = args.in[6] + (size_t)l * D * INW; K = D; N = INW; WT = (bf16*)(WL + OFF_WIN); rg = args.in[5] + (size_t)l * D; mode = 3; }
;             else { r -= I_IN; W = args.in[11] + (size_t)l * D * D; K = D; N = D; WT = (bf16*)(WL + OFF_WOUT); }
;             tr_item_cu(W, K, N, WT, rg, mode, lds + nbuf * TC_BUF, r, wave, lane);
;         }
.Ldc_setup:
	v_readlane_b32 s4, v255, 28
	v_readlane_b32 s0, v255, 62
	v_readlane_b32 s1, v255, 63
	v_readlane_b32 s12, v254, 0
	v_readlane_b32 s13, v254, 1
	v_mov_b32_e32 v2, v211
	s_cmp_lg_u32 s4, 0
	s_cselect_b32 s4, 2, 0
	s_and_b32 s5, s98, 3
	s_add_i32 s4, s4, s5
	s_lshr_b32 s5, s98, 2
	s_lshl_b32 s4, s4, 2
	s_or_b32 s4, s4, s5
	s_mov_b32 s99, 1
	s_mov_b32 s101, 0
	s_cmp_eq_u32 s4, 4
	s_cselect_b32 s99, 2272, s99
	s_cselect_b32 s101, 2495, s101
	s_cmp_eq_u32 s4, 5
	s_cselect_b32 s99, 2624, s99
	s_cselect_b32 s101, 3295, s101
	s_cmp_eq_u32 s4, 8
	s_cselect_b32 s99, 0, s99
	s_cselect_b32 s101, 127, s101
	s_cmp_eq_u32 s4, 9
	s_cselect_b32 s99, 1376, s99
	s_cselect_b32 s101, 2271, s101
	s_cmp_eq_u32 s4, 12
	s_cselect_b32 s99, 128, s99
	s_cselect_b32 s101, 383, s101
	s_cmp_eq_u32 s4, 13
	s_cselect_b32 s99, 736, s99
	s_cselect_b32 s101, 1375, s101
	s_cmp_eq_u32 s4, 16
	s_cselect_b32 s99, 384, s99
	s_cselect_b32 s101, 735, s101
	s_cmp_gt_i32 s99, s101
	s_cbranch_scc1 .Ldc_finish
	s_sub_i32 s5, s72, 0x80
	s_add_i32 s99, s99, s5
	s_cmp_gt_i32 s99, s101
	s_cbranch_scc1 .Ldc_nextpass
	s_movk_i32 s100, 0x80
	s_waitcnt lgkmcnt(0)
	s_nop 4
	s_branch .Ldc_pre
